# stack15: + grid-barrier census loads issued together
# baseline (speedup 1.0000x reference)
; __device__ __forceinline__ unsigned xb_ld(unsigned* p)              { return __hip_atomic_load(p, __ATOMIC_RELAXED, __HIP_MEMORY_SCOPE_AGENT); }
; __device__ __forceinline__ void xcd_barrier_complete(unsigned* bar, unsigned x, unsigned& nloc, unsigned& nx) {
;     const unsigned G = gridDim.x * gridDim.y * gridDim.z;
;     unsigned sum, cnt, mine, sp = 0u;
;     for (;;) {
;         sum = 0u; cnt = 0u; mine = 0u;
; #pragma unroll
;         for (unsigned j = 0; j < 16; ++j) { const unsigned c = xb_ld(&bar[XB_XCNT(j)]); sum += c; cnt += (c > 0u) ? 1u : 0u; mine = (j == x) ? c : mine; }
;         if (sum == G) break;
;         __builtin_amdgcn_s_sleep(1);
;         if ((++sp & 255u) == 0u) { if (xb_ld(&bar[XB_TMO])) break; if (sp > XB_SPIN_CAP) { atomicAdd(&bar[XB_TMO], 1u); break; } }
;     }
.LBB0_771:
	v_readlane_b32 s10, v253, 22
	v_readlane_b32 s11, v253, 23
	s_waitcnt lgkmcnt(0)
	s_nop 4
	global_load_dword v0, v153, s[36:37] sc1
	v_readlane_b32 s12, v254, 63
	s_nop 4
	global_load_dword v1, v153, s[10:11] sc1
	v_readlane_b32 s10, v253, 24
	v_readlane_b32 s11, v253, 25
	s_nop 4
	global_load_dword v2, v153, s[10:11] sc1
	v_readlane_b32 s10, v253, 26
	v_readlane_b32 s11, v253, 27
	s_nop 4
	global_load_dword v3, v153, s[10:11] sc1
	v_readlane_b32 s10, v253, 28
	v_readlane_b32 s11, v253, 29
	s_nop 4
	global_load_dword v4, v153, s[10:11] sc1
	v_readlane_b32 s10, v253, 30
	v_readlane_b32 s11, v253, 31
	s_nop 4
	global_load_dword v5, v153, s[10:11] sc1
	v_readlane_b32 s10, v253, 32
	v_readlane_b32 s11, v253, 33
	s_nop 4
	global_load_dword v6, v153, s[10:11] sc1
	v_readlane_b32 s10, v253, 34
	v_readlane_b32 s11, v253, 35
	s_nop 4
	global_load_dword v7, v153, s[10:11] sc1
	v_readlane_b32 s10, v253, 36
	v_readlane_b32 s11, v253, 37
	s_nop 4
	global_load_dword v8, v153, s[10:11] sc1
	v_readlane_b32 s10, v253, 38
	v_readlane_b32 s11, v253, 39
	s_nop 4
	global_load_dword v9, v153, s[10:11] sc1
	v_readlane_b32 s10, v253, 40
	v_readlane_b32 s11, v253, 41
	s_nop 4
	global_load_dword v10, v153, s[10:11] sc1
	v_readlane_b32 s10, v253, 42
	v_readlane_b32 s11, v253, 43
	s_nop 4
	global_load_dword v11, v153, s[10:11] sc1
	v_readlane_b32 s10, v253, 44
	v_readlane_b32 s11, v253, 45
	s_nop 4
	global_load_dword v12, v153, s[10:11] sc1
	v_readlane_b32 s10, v253, 46
	v_readlane_b32 s11, v253, 47
	s_nop 4
	global_load_dword v13, v153, s[10:11] sc1
	v_readlane_b32 s10, v253, 48
	v_readlane_b32 s11, v253, 49
	s_nop 4
	global_load_dword v14, v153, s[10:11] sc1
	v_readlane_b32 s10, v253, 50
	v_readlane_b32 s11, v253, 51
	s_nop 4
	global_load_dword v15, v153, s[10:11] sc1
	s_mov_b64 s[10:11], -1
	s_waitcnt vmcnt(0)
	v_add_u32_e32 v16, v1, v0
	v_add_u32_e32 v16, v16, v2
	v_add_u32_e32 v16, v16, v3
	v_add_u32_e32 v16, v16, v4
	v_add_u32_e32 v16, v16, v5
	v_add_u32_e32 v16, v16, v6
	v_add_u32_e32 v16, v16, v7
	v_add_u32_e32 v16, v16, v8
	v_add_u32_e32 v16, v16, v9
	v_add_u32_e32 v16, v16, v10
	v_add_u32_e32 v16, v16, v11
	v_add_u32_e32 v16, v16, v12
	v_add_u32_e32 v16, v16, v13
	v_add_u32_e32 v16, v16, v14
	v_add_u32_e32 v16, v16, v15
	v_cmp_eq_u32_e32 vcc, s12, v16
	s_mov_b64 s[12:13], -1
	s_cbranch_vccnz .LBB0_770
	s_and_b32 s10, s16, 0xff
	s_cmp_eq_u32 s10, 0
	s_mov_b64 s[10:11], -1
	s_mov_b64 s[14:15], -1
	s_sleep 1
	s_cbranch_scc0 .LBB0_775
	global_load_dword v16, v153, s[44:45] sc1
	s_waitcnt vmcnt(0)
	v_cmp_eq_u32_e32 vcc, 0, v16
	s_cbranch_vccnz .LBB0_777
	s_mov_b64 s[14:15], 0
